# first grid seam: cooperative-groups grid.sync replaced by the kernel's own XCD-hierarchical barrier (same release/acquire fences); on top of GEMM-loop edge edits, saddr DMA addresses and f8f6f4 fp8 GE
# speedup vs baseline: 1.0199x; 1.0040x over previous
; __device__ __forceinline__ unsigned xb_ld(unsigned* p)              { return __hip_atomic_load(p, __ATOMIC_RELAXED, __HIP_MEMORY_SCOPE_AGENT); }
; __device__ __forceinline__ void xcd_barrier_complete(unsigned* bar, unsigned x, unsigned& nloc, unsigned& nx) {
;     const unsigned G = gridDim.x * gridDim.y * gridDim.z;
;     unsigned sum, cnt, mine, sp = 0u;
;     for (;;) {
;         sum = 0u; cnt = 0u; mine = 0u;
; #pragma unroll
;         for (unsigned j = 0; j < 16; ++j) { const unsigned c = xb_ld(&bar[XB_XCNT(j)]); sum += c; cnt += (c > 0u) ? 1u : 0u; mine = (j == x) ? c : mine; }
; __device__ __forceinline__ void xcd_barrier(const XcdBarrier& b, const int tid) {
;     asm volatile("s_waitcnt vmcnt(0)" ::: "memory");
;     __syncthreads();
;     if (tid == 0) {
;         unsigned* bar = b.bar;
;         __builtin_amdgcn_s_waitcnt(0);
;         unsigned nloc = b.st[0], nx = b.st[1];
;         if (nloc == 0u) { xcd_barrier_complete(bar, b.x, nloc, nx); b.st[0] = nloc; b.st[1] = nx; }
.LBB0_212:
	s_waitcnt vmcnt(0) lgkmcnt(0)
	s_waitcnt vmcnt(0)
	s_waitcnt vmcnt(0)
	v_mbcnt_lo_u32_b32 v0, -1, 0
	v_mbcnt_hi_u32_b32 v0, -1, v0
	v_sub_u32_e32 v0, 0, v0
	v_cmp_eq_u32_e32 vcc, s33, v0
	s_barrier
	s_and_saveexec_b64 s[4:5], vcc
	s_cbranch_execz .Lgs0_298
	s_add_i32 s6, 0, 0x23a00
	v_mov_b32_e32 v0, s6
	s_waitcnt vmcnt(0) expcnt(0) lgkmcnt(0)
	ds_read_b32 v2, v0
	s_add_i32 s6, 0, 0x23a04
	v_mov_b32_e32 v0, s6
	ds_read_b32 v0, v0
	s_waitcnt lgkmcnt(1)
	v_cmp_ne_u32_e32 vcc, 0, v2
	s_cbranch_vccnz .Lgs0_258
	s_add_u32 s6, s36, 0x1000
	s_addc_u32 s7, s37, 0
	s_add_u32 s8, s36, 0x1100
	s_addc_u32 s9, s37, 0
	s_add_u32 s10, s36, 0x1200
	s_addc_u32 s11, s37, 0
	s_mul_i32 s20, s39, s93
	s_add_u32 s12, s36, 0x1300
	s_mul_i32 s20, s20, s38
	s_addc_u32 s13, s37, 0
	s_mov_b32 s21, 1
	v_mov_b32_e32 v16, 0
	s_branch .Lgs0_244

; __device__ __forceinline__ void xcd_barrier(const XcdBarrier& b, const int tid) {
;     ...
;         }
;     }
;     __syncthreads();
; }
.Lgs0_298:
	s_or_b64 exec, exec, s[4:5]
	s_waitcnt lgkmcnt(0)

; __global__ void __launch_bounds__(512, 2) fwd_megakernel(Params P) {
amdhsa.kernels:
  - .agpr_count:     0
    .args:
      - .offset:         0
        .size:           456
        .value_kind:     by_value
      - .offset:         456
        .size:           4
        .value_kind:     hidden_block_count_x
      - .offset:         460
        .size:           4
        .value_kind:     hidden_block_count_y
      - .offset:         464
        .size:           4
        .value_kind:     hidden_block_count_z
      - .offset:         468
        .size:           2
        .value_kind:     hidden_group_size_x
      - .offset:         470
        .size:           2
        .value_kind:     hidden_group_size_y
      - .offset:         472
        .size:           2
        .value_kind:     hidden_group_size_z
      - .offset:         474
        .size:           2
        .value_kind:     hidden_remainder_x
      - .offset:         476
        .size:           2
        .value_kind:     hidden_remainder_y
      - .offset:         478
        .size:           2
        .value_kind:     hidden_remainder_z
      - .offset:         496
        .size:           8
        .value_kind:     hidden_global_offset_x
      - .offset:         504
        .size:           8
        .value_kind:     hidden_global_offset_y
      - .offset:         512
        .size:           8
        .value_kind:     hidden_global_offset_z
      - .offset:         520
        .size:           2
        .value_kind:     hidden_grid_dims
      - .offset:         544
        .size:           8
        .value_kind:     hidden_multigrid_sync_arg
      - .offset:         576
        .size:           4
        .value_kind:     hidden_dynamic_lds_size
    .group_segment_fixed_size: 0
    .kernarg_segment_align: 8
    .kernarg_segment_size: 712
    .language:       OpenCL C
    .language_version:
      - 2
      - 0
    .max_flat_workgroup_size: 512
    .name:           _Z14fwd_megakernel6Params
    .private_segment_fixed_size: 0
    .sgpr_count:     108
    .sgpr_spill_count: 4
    .symbol:         _Z14fwd_megakernel6Params.kd
    .uniform_work_group_size: 1
    .uses_dynamic_stack: false
    .vgpr_count:     249
    .vgpr_spill_count: 0
    .wavefront_size: 64
